# attention: relative-position index/clamp arithmetic moved into the near-diagonal bias block (not executed on far tiles)
# speedup vs baseline: 1.0097x; 1.0048x over previous
.LBB0_677:
	s_add_i32 s2, s49, -2
	s_and_b32 s50, s2, 1
	v_lshl_add_u32 v10, s50, 14, v176
	v_lshl_add_u32 v145, v157, 4, v10
	v_lshl_add_u32 v144, v175, 4, v10
	ds_read_b128 v[2:5], v145
	ds_read_b128 v[6:9], v145 offset:256
	ds_read_b128 v[10:13], v144 offset:4096
	ds_read_b128 v[14:17], v144 offset:4352
	s_waitcnt lgkmcnt(3)
	v_mfma_f32_16x16x32_f16 v[2:5], v[2:5], v[36:39], 0
	v_cmp_gt_i32_e64 s[40:41], s24, v188
	s_waitcnt lgkmcnt(2)
	v_mfma_f32_16x16x32_f16 v[6:9], v[6:9], v[36:39], 0
	s_waitcnt lgkmcnt(0)
	v_mfma_f32_16x16x32_f16 v[22:25], v[14:17], v[40:43], v[6:9]
	v_mfma_f32_16x16x32_f16 v[18:21], v[10:13], v[40:43], v[2:5]
	s_nop 4
	v_add3_u32 v6, v189, s24, -15
	ds_read_b128 v[2:5], v145 offset:512
	ds_read_b128 v[10:13], v144 offset:4608
	v_max_i32_e32 v14, v6, v167
	ds_read_b128 v[6:9], v145 offset:768
	v_cmp_gt_i32_e32 vcc, s90, v14
	ds_read_b128 v[14:17], v144 offset:4864
	s_waitcnt lgkmcnt(3)
	v_mfma_f32_16x16x32_f16 v[2:5], v[2:5], v[36:39], 0
	s_waitcnt lgkmcnt(2)
	v_mfma_f32_16x16x32_f16 v[26:29], v[10:13], v[40:43], v[2:5]
	s_waitcnt lgkmcnt(1)
	v_mfma_f32_16x16x32_f16 v[2:5], v[6:9], v[36:39], 0
	s_waitcnt lgkmcnt(0)
	v_mfma_f32_16x16x32_f16 v[30:33], v[14:17], v[40:43], v[2:5]
	s_nop 3
	s_and_saveexec_b64 s[2:3], vcc
	s_xor_b64 s[2:3], exec, s[2:3]
	s_cbranch_execz .LBB0_679
	v_add_u32_e32 v10, s24, v165
	v_add_u32_e32 v11, 1, v10
	v_add_u32_e32 v12, 2, v10
	v_add_u32_e32 v6, 3, v10
	v_add_u32_e32 v7, 16, v10
	v_add_u32_e32 v8, 17, v10
	v_add_u32_e32 v9, 34, v10
	v_add_u32_e32 v13, 35, v10
	v_add_u32_e32 v14, 48, v10
	v_add_u32_e32 v2, 18, v10
	v_add_u32_e32 v3, 19, v10
	v_add_u32_e32 v4, 32, v10
	v_add_u32_e32 v5, 33, v10
	v_add_u32_e32 v15, 49, v10
	v_add_u32_e32 v16, 50, v10
	v_add_u32_e32 v17, 51, v10
	v_med3_i32 v211, v10, s87, v225
	v_med3_i32 v210, v11, s87, v225
	v_med3_i32 v209, v12, s87, v225
	v_med3_i32 v208, v6, s87, v225
	v_med3_i32 v207, v7, s87, v225
	v_med3_i32 v206, v8, s87, v225
	v_med3_i32 v205, v2, s87, v225
	v_med3_i32 v204, v3, s87, v225
	v_med3_i32 v203, v4, s87, v225
	v_med3_i32 v202, v5, s87, v225
	v_med3_i32 v201, v9, s87, v225
	v_med3_i32 v200, v13, s87, v225
	v_med3_i32 v199, v14, s87, v225
	v_med3_i32 v198, v15, s87, v225
	v_med3_i32 v197, v16, s87, v225
	v_med3_i32 v196, v17, s87, v225
	v_lshl_add_u32 v2, v203, 2, s91
	v_lshl_add_u32 v3, v202, 2, s91
	v_lshl_add_u32 v4, v201, 2, s91
	v_lshl_add_u32 v5, v200, 2, s91
	v_lshl_add_u32 v6, v199, 2, s91
	v_lshl_add_u32 v7, v198, 2, s91
	v_lshl_add_u32 v8, v197, 2, s91
	v_lshl_add_u32 v9, v196, 2, s91
	v_lshl_add_u32 v10, v211, 2, s91
	v_lshl_add_u32 v11, v210, 2, s91
	v_lshl_add_u32 v12, v209, 2, s91
	v_lshl_add_u32 v13, v208, 2, s91
	v_lshl_add_u32 v14, v207, 2, s91
	v_lshl_add_u32 v15, v206, 2, s91
	v_lshl_add_u32 v16, v205, 2, s91
	v_lshl_add_u32 v17, v204, 2, s91
	ds_read_b32 v2, v2 offset:512
	ds_read_b32 v3, v3 offset:512
	ds_read_b32 v4, v4 offset:512
	ds_read_b32 v5, v5 offset:512
	ds_read_b32 v6, v6 offset:512
	ds_read_b32 v7, v7 offset:512
	ds_read_b32 v8, v8 offset:512
	ds_read_b32 v9, v9 offset:512
	ds_read_b32 v132, v10 offset:512
	ds_read_b32 v133, v11 offset:512
	ds_read_b32 v134, v12 offset:512
	ds_read_b32 v135, v13 offset:512
	ds_read_b32 v136, v14 offset:512
	ds_read_b32 v137, v15 offset:512
	ds_read_b32 v138, v16 offset:512
	ds_read_b32 v139, v17 offset:512
	s_waitcnt lgkmcnt(8)
	v_fma_f32 v16, v32, s36, v8
	v_fma_f32 v17, v33, s36, v9
	v_fma_f32 v14, v30, s36, v6
	v_fma_f32 v15, v31, s36, v7
	v_fma_f32 v12, v28, s36, v4
	v_fma_f32 v13, v29, s36, v5
	v_fma_f32 v10, v26, s36, v2
	v_fma_f32 v11, v27, s36, v3
	s_waitcnt lgkmcnt(0)
	v_fma_f32 v8, v24, s36, v138
	v_fma_f32 v9, v25, s36, v139
	v_fma_f32 v6, v22, s36, v136
	v_fma_f32 v7, v23, s36, v137
	v_fma_f32 v4, v20, s36, v134
	v_fma_f32 v5, v21, s36, v135
	v_fma_f32 v2, v18, s36, v132
	v_fma_f32 v3, v19, s36, v133
